# token-shift: previous-row load no longer waited before the row loads are issued
# baseline (speedup 1.0000x reference)
; __device__ __forceinline__ float lo16(unsigned w) { return __uint_as_float(w << 16); }
; __device__ __forceinline__ float hi16(unsigned w) { return __uint_as_float(w & 0xffff0000u); }
; __device__ void phase_prep(const Ctx& p, int l, LAS unsigned char* lds) {
;     ...
;             } else {
;                 const u32x4 w = *(const u32x4*)(PR + (size_t)(t0 + rstart - 1) * 2048 + c0);
;                 prev[0] = lo16(w.x); prev[1] = hi16(w.x); prev[2] = lo16(w.y); prev[3] = hi16(w.y); prev[4] = lo16(w.z); prev[5] = hi16(w.z); prev[6] = lo16(w.w); prev[7] = hi16(w.w);
;             }
.LBB0_610:
	s_or_b64 exec, exec, s[62:63]
	v_mov_b32_e32 v226, 0
	s_and_saveexec_b64 s[14:15], vcc
	s_xor_b64 s[62:63], exec, s[14:15]
	s_cbranch_execz .LBB0_612
	v_add_u32_e32 v8, s76, v161
	v_ashrrev_i32_e32 v9, 31, v8
	v_lshlrev_b64 v[8:9], 12, v[8:9]
	v_lshl_add_u64 v[8:9], v[88:89], 0, v[8:9]
	global_load_dwordx4 v[222:225], v[8:9], off
	v_mov_b32_e32 v226, 1
	s_andn2_b64 s[60:61], s[60:61], exec
	s_or_b64 exec, exec, s[62:63]
	s_and_saveexec_b64 s[62:63], s[60:61]
	s_cbranch_execz .LBB0_616
	s_branch .LBB0_613

; __device__ __forceinline__ float sigm(float x) { return __builtin_amdgcn_rcpf(1.0f + __expf(-x)); }
; __device__ __forceinline__ float tanh_fast(float x) { return 1.0f - 2.0f * __builtin_amdgcn_rcpf(1.0f + __expf(2.0f * x)); }
; __device__ __forceinline__ float lo16(unsigned w) { return __uint_as_float(w << 16); }
; __device__ __forceinline__ float hi16(unsigned w) { return __uint_as_float(w & 0xffff0000u); }
; __device__ void phase_prep(const Ctx& p, int l, LAS unsigned char* lds) {
;     ...
;                 const u32x4 w = *(const u32x4*)(PR + (size_t)(t0 + rstart - 1) * 2048 + c0);
;                 prev[0] = lo16(w.x); prev[1] = hi16(w.x); prev[2] = lo16(w.y); prev[3] = hi16(w.y); prev[4] = lo16(w.z); prev[5] = hi16(w.z); prev[6] = lo16(w.w); prev[7] = hi16(w.w);
;     ...
;             for (int r8 = 0; r8 < 16; r8 += 8) {
;             u32x4 wrow[8];
; #pragma unroll
;             for (int r = 0; r < 8; ++r) wrow[r] = *(const u32x4*)(PR + (size_t)(t0 + rstart + r8 + r) * 2048 + c0);
; #pragma unroll
;             for (int rr = 0; rr < 8; ++rr) {
;                 const int r = r8 + rr; const u32x4 w = wrow[rr];
;                 float cur[8], o[8];
;                 cur[0] = lo16(w.x); cur[1] = hi16(w.x); cur[2] = lo16(w.y); cur[3] = hi16(w.y); cur[4] = lo16(w.z); cur[5] = hi16(w.z); cur[6] = lo16(w.w); cur[7] = hi16(w.w);
; #pragma unroll
;                 for (int j = 0; j < 8; ++j) { float x = cur[j] + (prev[j] - cur[j]) * m8[j]; if (fn == 1) x = tanh_fast(x); else if (fn == 2) x = sigm(x); o[j] = x; prev[j] = cur[j]; }
.LBB0_619:
	s_mov_b64 s[60:61], exec
	v_cmp_eq_u32_e64 s[62:63], 1, v162
	v_cmp_eq_u32_e64 s[64:65], 2, v162
	s_mov_b64 s[14:15], 0x1000
	v_or_b32_e32 v216, s10, v48
	v_mov_b32_e32 v217, 0
	v_lshlrev_b64 v[218:219], 12, v[216:217]
	v_lshl_add_u64 v[218:219], v[88:89], 0, v[218:219]
	global_load_dwordx4 v[44:47], v[218:219], off
	v_lshl_add_u64 v[218:219], v[218:219], 0, s[14:15]
	global_load_dwordx4 v[32:35], v[218:219], off
	v_lshl_add_u64 v[218:219], v[218:219], 0, s[14:15]
	global_load_dwordx4 v[28:31], v[218:219], off
	v_lshl_add_u64 v[218:219], v[218:219], 0, s[14:15]
	global_load_dwordx4 v[24:27], v[218:219], off
	v_lshl_add_u64 v[218:219], v[218:219], 0, s[14:15]
	global_load_dwordx4 v[20:23], v[218:219], off
	v_lshl_add_u64 v[218:219], v[218:219], 0, s[14:15]
	global_load_dwordx4 v[16:19], v[218:219], off
	v_lshl_add_u64 v[218:219], v[218:219], 0, s[14:15]
	global_load_dwordx4 v[12:15], v[218:219], off
	v_lshl_add_u64 v[218:219], v[218:219], 0, s[14:15]
	global_load_dwordx4 v[8:11], v[218:219], off
	v_or_b32_e32 v220, s10, v160
	v_mul_lo_u32 v220, v220, s75
	v_add_u32_e32 v220, v163, v220
	s_waitcnt vmcnt(7)
	s_cmp_lg_u32 s10, 0
	s_cbranch_scc1 .Lshift_pv
	v_cmp_eq_u32_e32 vcc, 1, v226
	s_nop 1
	s_and_saveexec_b64 s[16:17], vcc
	v_lshlrev_b32_e32 v40, 16, v222
	v_and_b32_e32 v41, 0xffff0000, v222
	v_lshlrev_b32_e32 v42, 16, v223
	v_and_b32_e32 v43, 0xffff0000, v223
	v_lshlrev_b32_e32 v36, 16, v224
	v_and_b32_e32 v37, 0xffff0000, v224
	v_lshlrev_b32_e32 v38, 16, v225
	v_and_b32_e32 v39, 0xffff0000, v225
	s_mov_b64 exec, s[16:17]
.Lshift_pv:
	v_lshlrev_b32_e32 v196, 16, v44
	v_and_b32_e32 v197, 0xffff0000, v44
	v_lshlrev_b32_e32 v198, 16, v45
	v_and_b32_e32 v199, 0xffff0000, v45
	v_lshlrev_b32_e32 v200, 16, v46
	v_and_b32_e32 v201, 0xffff0000, v46
	v_lshlrev_b32_e32 v202, 16, v47
	v_and_b32_e32 v203, 0xffff0000, v47
	v_sub_f32_e32 v40, v40, v196
	v_sub_f32_e32 v41, v41, v197
	v_sub_f32_e32 v42, v42, v198
	v_sub_f32_e32 v43, v43, v199
	v_sub_f32_e32 v36, v36, v200
	v_sub_f32_e32 v37, v37, v201
	v_sub_f32_e32 v38, v38, v202
	v_sub_f32_e32 v39, v39, v203
	v_fma_f32 v40, v4, v40, v196
	v_fma_f32 v41, v5, v41, v197
	v_fma_f32 v42, v6, v42, v198
	v_fma_f32 v43, v7, v43, v199
	v_fma_f32 v36, v0, v36, v200
	v_fma_f32 v37, v1, v37, v201
	v_fma_f32 v38, v2, v38, v202
	v_fma_f32 v39, v3, v39, v203
	s_cmp_lg_u64 s[62:63], 0
	s_cbranch_scc0 .Lshift_nt0
	s_mov_b64 exec, s[62:63]
	v_add_f32_e32 v40, v40, v40
	v_add_f32_e32 v41, v41, v41
	v_add_f32_e32 v42, v42, v42
	v_add_f32_e32 v43, v43, v43
	v_add_f32_e32 v36, v36, v36
	v_add_f32_e32 v37, v37, v37
	v_add_f32_e32 v38, v38, v38
	v_add_f32_e32 v39, v39, v39
	v_mul_f32_e32 v40, 0x3fb8aa3b, v40
	v_mul_f32_e32 v41, 0x3fb8aa3b, v41
	v_mul_f32_e32 v42, 0x3fb8aa3b, v42
	v_mul_f32_e32 v43, 0x3fb8aa3b, v43
	v_mul_f32_e32 v36, 0x3fb8aa3b, v36
	v_mul_f32_e32 v37, 0x3fb8aa3b, v37
	v_mul_f32_e32 v38, 0x3fb8aa3b, v38
	v_mul_f32_e32 v39, 0x3fb8aa3b, v39
	v_exp_f32_e32 v40, v40
	v_exp_f32_e32 v41, v41
	v_exp_f32_e32 v42, v42
	v_exp_f32_e32 v43, v43
	v_exp_f32_e32 v36, v36
	v_exp_f32_e32 v37, v37
	v_exp_f32_e32 v38, v38
	v_exp_f32_e32 v39, v39
	v_add_f32_e32 v40, 1.0, v40
	v_add_f32_e32 v41, 1.0, v41
	v_add_f32_e32 v42, 1.0, v42
	v_add_f32_e32 v43, 1.0, v43
	v_add_f32_e32 v36, 1.0, v36
	v_add_f32_e32 v37, 1.0, v37
	v_add_f32_e32 v38, 1.0, v38
	v_add_f32_e32 v39, 1.0, v39
	v_rcp_f32_e32 v40, v40
	v_rcp_f32_e32 v41, v41
	v_rcp_f32_e32 v42, v42
	v_rcp_f32_e32 v43, v43
	v_rcp_f32_e32 v36, v36
	v_rcp_f32_e32 v37, v37
	v_rcp_f32_e32 v38, v38
	v_rcp_f32_e32 v39, v39
	v_fma_f32 v40, v40, -2.0, 1.0
	v_fma_f32 v41, v41, -2.0, 1.0
	v_fma_f32 v42, v42, -2.0, 1.0
	v_fma_f32 v43, v43, -2.0, 1.0
	v_fma_f32 v36, v36, -2.0, 1.0
	v_fma_f32 v37, v37, -2.0, 1.0
	v_fma_f32 v38, v38, -2.0, 1.0
	v_fma_f32 v39, v39, -2.0, 1.0
	s_mov_b64 exec, s[60:61]
